# counted wait in the hand-written rowpass: Y loads issued before the h loads, y^2 reduction + rstd run behind vmcnt(8) while the residual row is still arriving
# speedup vs baseline: 1.0038x; 1.0012x over previous
; __device__ __forceinline__ void phase_rowpass(const KArgs& A, int l, int wave, int lane, bool dummy = false) {
;     ...
;     for (int r = r0; r < r1; r += rs) {
;         const int b = r / TB, t = r % TB; const bool lat = t < SEQ; const int v = lat ? b : 8;
;         if (last && !lat) continue;
;         const size_t hoff = lat ? ((size_t)b * SEQ + t) * DM : ((size_t)b * CTXL + (t - SEQ)) * DM;
;         const float* hin = (l <= 1 ? (lat ? A.in[0] : A.in[2]) : (lat ? (const float*)A.out : (const float*)hctx)) + hoff;
;         float* hout = dummy ? (float*)(A.ws + OFF_K) + (size_t)r * DM : (lat ? A.out : hctx) + hoff;
;         f32x4 h[8];
; #pragma unroll
;         for (int j = 0; j < 8; ++j) h[j] = *(const f32x4*)(hin + 4 * lane + 256 * j);
;         if (!first) {
;             f32x4 y[8]; float ss = 0.f;
; #pragma unroll
;             for (int j = 0; j < 8; ++j) {
;                 if (lat || !GOUT_SPLIT) { const v2u w = *(const v2u*)(Y + (size_t)r * DM + 4 * lane + 256 * j); y[j] = (f32x4){bflo(w.x), bfhi(w.x), bflo(w.y), bfhi(w.y)}; }
.Lrp_loop:
	s_mul_hi_i32 s20, s12, 0x38e38e39
	s_lshr_b32 s21, s20, 31
	s_ashr_i32 s20, s20, 9
	s_add_i32 s20, s20, s21
	s_mul_i32 s21, s20, 0xfffff700
	s_add_i32 s21, s12, s21
	s_cmpk_lt_i32 s21, 0x800
	s_cselect_b64 s[38:39], -1, 0
	s_or_b64 s[38:39], s[10:11], s[38:39]
	s_and_b64 vcc, exec, s[38:39]
	s_cbranch_vccz .Lrp_next
	s_lshl_b32 s25, s12, 12
	s_and_b64 vcc, exec, s[6:7]
	s_cbranch_vccz .Lrp_noy
	s_add_u32 s38, s94, s25
	s_addc_u32 s39, s95, 0
	s_add_u32 s38, s38, 0xe400000
	s_addc_u32 s39, s39, 0
	global_load_dwordx2 v[34:35], v179, s[38:39]
	global_load_dwordx2 v[36:37], v179, s[38:39] offset:512
	global_load_dwordx2 v[38:39], v179, s[38:39] offset:1024
	global_load_dwordx2 v[40:41], v179, s[38:39] offset:1536
	global_load_dwordx2 v[42:43], v179, s[38:39] offset:2048
	global_load_dwordx2 v[44:45], v179, s[38:39] offset:2560
	global_load_dwordx2 v[46:47], v179, s[38:39] offset:3072
	global_load_dwordx2 v[48:49], v179, s[38:39] offset:3584
.Lrp_noy:
	s_lshl_b32 s22, s20, 11
	s_add_i32 s22, s22, s21
	s_lshl_b32 s23, s20, 8
	s_add_i32 s23, s23, s21
	s_addk_i32 s23, 0xf800
	s_cmpk_lt_i32 s21, 0x800
	s_cselect_b32 s22, s22, s23
	s_cselect_b32 s24, s20, 8
	s_cselect_b32 s38, s14, s16
	s_cselect_b32 s39, s15, s17
	s_cselect_b64 s[20:21], -1, 0
	s_lshl_b32 s22, s22, 13
	s_add_u32 s38, s38, s22
	s_addc_u32 s39, s39, 0
	global_load_dwordx4 v[2:5], v178, s[38:39]
	global_load_dwordx4 v[6:9], v178, s[38:39] offset:1024
	global_load_dwordx4 v[10:13], v178, s[38:39] offset:2048
	global_load_dwordx4 v[14:17], v178, s[38:39] offset:3072
	global_load_dwordx4 v[18:21], v180, s[38:39]
	global_load_dwordx4 v[22:25], v180, s[38:39] offset:1024
	global_load_dwordx4 v[26:29], v180, s[38:39] offset:2048
	global_load_dwordx4 v[30:33], v180, s[38:39] offset:3072
	s_add_u32 s38, s94, 0x8900000
	s_addc_u32 s39, s95, 0
	s_cmp_lg_u64 s[20:21], 0
	s_cselect_b32 s38, s18, s38
	s_cselect_b32 s39, s19, s39
	s_add_u32 s22, s38, s22
	s_addc_u32 s23, s39, 0
	s_cmp_eq_u32 s24, s13
	s_cbranch_scc1 .Lrp_vec_ok
	s_mov_b32 s13, s24
	s_and_b64 vcc, exec, s[6:7]
	s_cbranch_vccz .Lrp_nogate
	s_add_i32 s38, s30, s24
	s_mul_i32 s38, s38, 0x6000
	s_add_i32 s38, s38, 0x4000
	s_add_u32 s38, s94, s38
	s_addc_u32 s39, s95, 0
	global_load_dwordx4 v[50:53], v178, s[38:39]
	global_load_dwordx4 v[54:57], v178, s[38:39] offset:1024
	global_load_dwordx4 v[58:61], v178, s[38:39] offset:2048
	global_load_dwordx4 v[62:65], v178, s[38:39] offset:3072
	global_load_dwordx4 v[66:69], v180, s[38:39]
	global_load_dwordx4 v[70:73], v180, s[38:39] offset:1024
	global_load_dwordx4 v[74:77], v180, s[38:39] offset:2048
	global_load_dwordx4 v[78:81], v180, s[38:39] offset:3072

; __device__ __forceinline__ void phase_rowpass(const KArgs& A, int l, int wave, int lane, bool dummy = false) {
;     ...
;         if (!first) {
;             f32x4 y[8]; float ss = 0.f;
; #pragma unroll
;             for (int j = 0; j < 8; ++j) {
;                 if (lat || !GOUT_SPLIT) { const v2u w = *(const v2u*)(Y + (size_t)r * DM + 4 * lane + 256 * j); y[j] = (f32x4){bflo(w.x), bfhi(w.x), bflo(w.y), bfhi(w.y)}; }
;                 else { y[j] = (f32x4){0.f, 0.f, 0.f, 0.f};
; #pragma unroll
;                     for (int kq = 0; kq < 4; ++kq) { const v2u w = *(const v2u*)((const bf16_t*)(A.ws + OFF_V) + ((size_t)kq * 2048 + (size_t)b * CTXL + (t - SEQ)) * DM + 4 * lane + 256 * j);
;                         y[j] += (f32x4){bflo(w.x), bfhi(w.x), bflo(w.y), bfhi(w.y)}; } }
;                 ss += (y[j].x * y[j].x + y[j].y * y[j].y) + (y[j].z * y[j].z + y[j].w * y[j].w); }
;             const float rstd = 1.f / sqrtf(wave_sum(ss) * (1.f / DM) + NORM_EPS);
.Lrp_vec_ok:
	s_add_u32 s24, s94, s25
	s_addc_u32 s25, s95, 0
	s_add_u32 s24, s24, 0x9c00000
	s_addc_u32 s25, s25, 0
	s_and_b64 vcc, exec, s[6:7]
	s_cbranch_vccnz .Lrp_first_half
	s_waitcnt vmcnt(0)
	s_branch .Lrp_second
.Lrp_first_half:
	s_waitcnt vmcnt(8)
	v_lshlrev_b32_e32 v228, 16, v34
	v_and_b32_e32 v229, s3, v34
	v_mul_f32_e32 v224, v228, v228
	v_mul_f32_e32 v225, v229, v229
	v_lshlrev_b32_e32 v228, 16, v35
	v_and_b32_e32 v229, s3, v35
	v_mul_f32_e32 v226, v228, v228
	v_mul_f32_e32 v227, v229, v229
	v_lshlrev_b32_e32 v228, 16, v36
	v_and_b32_e32 v229, s3, v36
	v_fmac_f32_e32 v224, v228, v228
	v_fmac_f32_e32 v225, v229, v229
	v_lshlrev_b32_e32 v228, 16, v37
	v_and_b32_e32 v229, s3, v37
	v_fmac_f32_e32 v226, v228, v228
	v_fmac_f32_e32 v227, v229, v229
	v_lshlrev_b32_e32 v228, 16, v38
	v_and_b32_e32 v229, s3, v38
	v_fmac_f32_e32 v224, v228, v228
	v_fmac_f32_e32 v225, v229, v229
	v_lshlrev_b32_e32 v228, 16, v39
	v_and_b32_e32 v229, s3, v39
	v_fmac_f32_e32 v226, v228, v228
	v_fmac_f32_e32 v227, v229, v229
	v_lshlrev_b32_e32 v228, 16, v40
	v_and_b32_e32 v229, s3, v40
	v_fmac_f32_e32 v224, v228, v228
	v_fmac_f32_e32 v225, v229, v229
	v_lshlrev_b32_e32 v228, 16, v41
	v_and_b32_e32 v229, s3, v41
	v_fmac_f32_e32 v226, v228, v228
	v_fmac_f32_e32 v227, v229, v229
	v_lshlrev_b32_e32 v228, 16, v42
	v_and_b32_e32 v229, s3, v42
	v_fmac_f32_e32 v224, v228, v228
	v_fmac_f32_e32 v225, v229, v229
	v_lshlrev_b32_e32 v228, 16, v43
	v_and_b32_e32 v229, s3, v43
	v_fmac_f32_e32 v226, v228, v228
	v_fmac_f32_e32 v227, v229, v229
	v_lshlrev_b32_e32 v228, 16, v44
	v_and_b32_e32 v229, s3, v44
	v_fmac_f32_e32 v224, v228, v228
	v_fmac_f32_e32 v225, v229, v229
	v_lshlrev_b32_e32 v228, 16, v45
	v_and_b32_e32 v229, s3, v45
	v_fmac_f32_e32 v226, v228, v228
	v_fmac_f32_e32 v227, v229, v229
	v_lshlrev_b32_e32 v228, 16, v46
	v_and_b32_e32 v229, s3, v46
	v_fmac_f32_e32 v224, v228, v228
	v_fmac_f32_e32 v225, v229, v229
	v_lshlrev_b32_e32 v228, 16, v47
	v_and_b32_e32 v229, s3, v47
	v_fmac_f32_e32 v226, v228, v228
	v_fmac_f32_e32 v227, v229, v229
	v_lshlrev_b32_e32 v228, 16, v48
	v_and_b32_e32 v229, s3, v48
	v_fmac_f32_e32 v224, v228, v228
	v_fmac_f32_e32 v225, v229, v229
	v_lshlrev_b32_e32 v228, 16, v49
	v_and_b32_e32 v229, s3, v49
	v_fmac_f32_e32 v226, v228, v228
	v_fmac_f32_e32 v227, v229, v229
	v_add_f32_e32 v224, v224, v225
	v_add_f32_e32 v226, v226, v227
	v_add_f32_e32 v224, v224, v226
	s_nop 1
	v_add_f32_dpp v224, v224, v224 quad_perm:[1,0,3,2] row_mask:0xf bank_mask:0xf
	s_nop 1
	v_add_f32_dpp v224, v224, v224 quad_perm:[2,3,0,1] row_mask:0xf bank_mask:0xf
	s_nop 1
	v_add_f32_dpp v224, v224, v224 row_half_mirror row_mask:0xf bank_mask:0xf
	s_nop 1
	v_add_f32_dpp v224, v224, v224 row_mirror row_mask:0xf bank_mask:0xf
	s_nop 1
	v_readlane_b32 s20, v224, 0
	v_readlane_b32 s21, v224, 16
	v_readlane_b32 s38, v224, 32
	v_readlane_b32 s39, v224, 48
	s_nop 2
	v_mov_b32_e32 v224, s20
	v_add_f32_e32 v224, s21, v224
	v_add_f32_e32 v224, s38, v224
	v_add_f32_e32 v224, s39, v224
	v_fmamk_f32 v240, v224, 0x3a000000, v186
	v_mul_f32_e32 v241, 0x4f800000, v240
	v_cmp_gt_f32_e32 vcc, s54, v240
	s_nop 1
	v_cndmask_b32_e32 v240, v240, v241, vcc
	v_sqrt_f32_e32 v241, v240
	s_nop 0
	v_add_u32_e32 v242, -1, v241
	v_fma_f32 v243, -v242, v241, v240
	v_cmp_ge_f32_e64 s[38:39], 0, v243
	v_add_u32_e32 v243, 1, v241
	s_nop 0
	v_cndmask_b32_e64 v242, v241, v242, s[38:39]
	v_fma_f32 v241, -v243, v241, v240
	v_cmp_lt_f32_e64 s[38:39], 0, v241
	s_nop 1
	v_cndmask_b32_e64 v241, v242, v243, s[38:39]
	v_mul_f32_e32 v242, 0x37800000, v241
	v_cndmask_b32_e32 v241, v241, v242, vcc
	v_cmp_class_f32_e32 vcc, v240, v187
	s_nop 1
	v_cndmask_b32_e32 v240, v241, v240, vcc
	v_div_scale_f32 v241, s[20:21], v240, v240, 1.0
	v_rcp_f32_e32 v242, v241
	s_nop 0
	v_fma_f32 v243, -v241, v242, 1.0
	v_fmac_f32_e32 v242, v243, v242
	v_div_scale_f32 v243, vcc, 1.0, v240, 1.0
	v_mul_f32_e32 v244, v243, v242
	v_fma_f32 v245, -v241, v244, v243
	v_fmac_f32_e32 v244, v245, v242
	v_fma_f32 v241, -v241, v244, v243
	v_div_fmas_f32 v241, v241, v242, v244
	v_div_fixup_f32 v230, v241, v240, 1.0
	s_waitcnt vmcnt(0)
; __device__ __forceinline__ void phase_rowpass(const KArgs& A, int l, int wave, int lane, bool dummy = false) {
;     ...
; #pragma unroll
;             for (int j = 0; j < 8; ++j) { const int c = 4 * lane + 256 * j; const f32x4 gt = *(const f32x4*)(gate + c), pg = *(const f32x4*)(post_g + c);
;                 h[j] += gt * (y[j] * rstd * pg); *(f32x4*)(hout + c) = h[j]; }
	v_lshlrev_b32_e32 v224, 16, v34
	v_and_b32_e32 v225, s3, v34
	v_lshlrev_b32_e32 v226, 16, v35
	v_and_b32_e32 v227, s3, v35
	v_pk_mul_f32 v[224:225], v[230:231], v[224:225] op_sel_hi:[0,1]
	v_pk_mul_f32 v[226:227], v[230:231], v[226:227] op_sel_hi:[0,1]
	v_pk_mul_f32 v[224:225], v[82:83], v[224:225]
	v_pk_mul_f32 v[226:227], v[84:85], v[226:227]
	v_pk_fma_f32 v[2:3], v[50:51], v[224:225], v[2:3]
	v_pk_fma_f32 v[4:5], v[52:53], v[226:227], v[4:5]
	global_store_dwordx4 v178, v[2:5], s[22:23]
	v_lshlrev_b32_e32 v224, 16, v36
	v_and_b32_e32 v225, s3, v36
	v_lshlrev_b32_e32 v226, 16, v37
	v_and_b32_e32 v227, s3, v37
	v_pk_mul_f32 v[224:225], v[230:231], v[224:225] op_sel_hi:[0,1]
	v_pk_mul_f32 v[226:227], v[230:231], v[226:227] op_sel_hi:[0,1]
	v_pk_mul_f32 v[224:225], v[86:87], v[224:225]
	v_pk_mul_f32 v[226:227], v[88:89], v[226:227]
	v_pk_fma_f32 v[6:7], v[54:55], v[224:225], v[6:7]
	v_pk_fma_f32 v[8:9], v[56:57], v[226:227], v[8:9]
	global_store_dwordx4 v178, v[6:9], s[22:23] offset:1024
	v_lshlrev_b32_e32 v224, 16, v38
	v_and_b32_e32 v225, s3, v38
	v_lshlrev_b32_e32 v226, 16, v39
	v_and_b32_e32 v227, s3, v39
	v_pk_mul_f32 v[224:225], v[230:231], v[224:225] op_sel_hi:[0,1]
	v_pk_mul_f32 v[226:227], v[230:231], v[226:227] op_sel_hi:[0,1]
	v_pk_mul_f32 v[224:225], v[90:91], v[224:225]
	v_pk_mul_f32 v[226:227], v[92:93], v[226:227]
	v_pk_fma_f32 v[10:11], v[58:59], v[224:225], v[10:11]
	v_pk_fma_f32 v[12:13], v[60:61], v[226:227], v[12:13]
	global_store_dwordx4 v178, v[10:13], s[22:23] offset:2048
	v_lshlrev_b32_e32 v224, 16, v40
	v_and_b32_e32 v225, s3, v40
	v_lshlrev_b32_e32 v226, 16, v41
	v_and_b32_e32 v227, s3, v41
	v_pk_mul_f32 v[224:225], v[230:231], v[224:225] op_sel_hi:[0,1]
	v_pk_mul_f32 v[226:227], v[230:231], v[226:227] op_sel_hi:[0,1]
	v_pk_mul_f32 v[224:225], v[94:95], v[224:225]
	v_pk_mul_f32 v[226:227], v[96:97], v[226:227]
	v_pk_fma_f32 v[14:15], v[62:63], v[224:225], v[14:15]
	v_pk_fma_f32 v[16:17], v[64:65], v[226:227], v[16:17]
	global_store_dwordx4 v178, v[14:17], s[22:23] offset:3072
	v_lshlrev_b32_e32 v224, 16, v42
	v_and_b32_e32 v225, s3, v42
	v_lshlrev_b32_e32 v226, 16, v43
	v_and_b32_e32 v227, s3, v43
	v_pk_mul_f32 v[224:225], v[230:231], v[224:225] op_sel_hi:[0,1]
	v_pk_mul_f32 v[226:227], v[230:231], v[226:227] op_sel_hi:[0,1]
	v_pk_mul_f32 v[224:225], v[98:99], v[224:225]
	v_pk_mul_f32 v[226:227], v[100:101], v[226:227]
	v_pk_fma_f32 v[18:19], v[66:67], v[224:225], v[18:19]
	v_pk_fma_f32 v[20:21], v[68:69], v[226:227], v[20:21]
	global_store_dwordx4 v180, v[18:21], s[22:23]
	v_lshlrev_b32_e32 v224, 16, v44
	v_and_b32_e32 v225, s3, v44
	v_lshlrev_b32_e32 v226, 16, v45
	v_and_b32_e32 v227, s3, v45
	v_pk_mul_f32 v[224:225], v[230:231], v[224:225] op_sel_hi:[0,1]
	v_pk_mul_f32 v[226:227], v[230:231], v[226:227] op_sel_hi:[0,1]
	v_pk_mul_f32 v[224:225], v[102:103], v[224:225]
	v_pk_mul_f32 v[226:227], v[104:105], v[226:227]
	v_pk_fma_f32 v[22:23], v[70:71], v[224:225], v[22:23]
	v_pk_fma_f32 v[24:25], v[72:73], v[226:227], v[24:25]
	global_store_dwordx4 v180, v[22:25], s[22:23] offset:1024
	v_lshlrev_b32_e32 v224, 16, v46
	v_and_b32_e32 v225, s3, v46
	v_lshlrev_b32_e32 v226, 16, v47
	v_and_b32_e32 v227, s3, v47
	v_pk_mul_f32 v[224:225], v[230:231], v[224:225] op_sel_hi:[0,1]
	v_pk_mul_f32 v[226:227], v[230:231], v[226:227] op_sel_hi:[0,1]
	v_pk_mul_f32 v[224:225], v[106:107], v[224:225]
	v_pk_mul_f32 v[226:227], v[108:109], v[226:227]
	v_pk_fma_f32 v[26:27], v[74:75], v[224:225], v[26:27]
	v_pk_fma_f32 v[28:29], v[76:77], v[226:227], v[28:29]
	global_store_dwordx4 v180, v[26:29], s[22:23] offset:2048
	v_lshlrev_b32_e32 v224, 16, v48
	v_and_b32_e32 v225, s3, v48
	v_lshlrev_b32_e32 v226, 16, v49
	v_and_b32_e32 v227, s3, v49
	v_pk_mul_f32 v[224:225], v[230:231], v[224:225] op_sel_hi:[0,1]
	v_pk_mul_f32 v[226:227], v[230:231], v[226:227] op_sel_hi:[0,1]
	v_pk_mul_f32 v[224:225], v[110:111], v[224:225]
	v_pk_mul_f32 v[226:227], v[112:113], v[226:227]
	v_pk_fma_f32 v[30:31], v[78:79], v[224:225], v[30:31]
	v_pk_fma_f32 v[32:33], v[80:81], v[226:227], v[32:33]
	global_store_dwordx4 v180, v[30:33], s[22:23] offset:3072
